# bh2 + nt cache policy on the post section's once-read dwordx4 streaming loads
# baseline (speedup 1.0000x reference)
; __global__ void __launch_bounds__(NWAVES * 64, 2) fwd(Args args_unused) {
;     ...
;             for (int row0 = gw; row0 < M; row0 += 2 * NGW) {
;                 const int hh = lane >> 3;
;                 float l0[2], l1[2], l2[2]; v4u r0[2], r1[2], r2[2], yr[2][2], zr[2][2];
; #pragma unroll
;                 for (int k = 0; k < 2; ++k) { const int row = row0 + k * NGW;
;                     l0[k] = 0.f; l1[k] = 0.f; l2[k] = 0.f; r0[k] = (v4u){0u, 0u, 0u, 0u}; r1[k] = (v4u){0u, 0u, 0u, 0u}; r2[k] = (v4u){0u, 0u, 0u, 0u};
; #pragma unroll
;                     for (int q = 0; q < 2; ++q) { yr[k][q] = (v4u){0u, 0u, 0u, 0u}; zr[k][q] = (v4u){0u, 0u, 0u, 0u}; }
;                     if (row < M) {
;                         l0[k] = LSE[((size_t)0 * M + row) * 8 + hh]; l1[k] = LSE[((size_t)1 * M + row) * 8 + hh]; l2[k] = LSE[((size_t)2 * M + row) * 8 + hh];
;                         r0[k] = *(const v4u*)(OG + ((size_t)0 * M + row) * 512 + 8 * lane); r1[k] = *(const v4u*)(OG + ((size_t)1 * M + row) * 512 + 8 * lane); r2[k] = *(const v4u*)(OG + ((size_t)2 * M + row) * 512 + 8 * lane);
; #pragma unroll
;                         for (int q = 0; q < 2; ++q) { const int col = q * 512 + 8 * lane; yr[k][q] = *(const v4u*)(YS + (size_t)row * DM + col); zr[k][q] = *(const v4u*)ZP(Z, row, ZZB + col); } } }
.LBB0_1926:
	s_ashr_i32 s5, s4, 31
	s_lshl_b64 s[6:7], s[4:5], 5
	v_lshl_add_u64 v[18:19], v[76:77], 0, s[6:7]
	s_add_u32 s6, s4, 0x8100
	s_addc_u32 s7, s5, 0
	s_lshl_b64 s[8:9], s[6:7], 5
	v_lshl_add_u64 v[20:21], v[76:77], 0, s[8:9]
	s_add_u32 s8, s4, 0x10200
	s_addc_u32 s9, s5, 0
	s_lshl_b64 s[10:11], s[8:9], 5
	v_lshl_add_u64 v[22:23], v[76:77], 0, s[10:11]
	s_lshl_b64 s[10:11], s[4:5], 10
	s_lshl_b64 s[6:7], s[6:7], 10
	v_lshl_add_u64 v[24:25], v[78:79], 0, s[10:11]
	global_load_dword v96, v[18:19], off
	global_load_dword v95, v[20:21], off
	global_load_dword v94, v[22:23], off
	global_load_dwordx4 v[62:65], v[24:25], off nt
	v_lshl_add_u64 v[18:19], v[78:79], 0, s[6:7]
	s_lshl_b64 s[6:7], s[8:9], 10
	v_lshl_add_u64 v[20:21], v[78:79], 0, s[6:7]
	s_lshl_b64 s[6:7], s[4:5], 11
	global_load_dwordx4 v[70:73], v[18:19], off nt
	global_load_dwordx4 v[66:69], v[20:21], off nt
	v_lshl_add_u64 v[18:19], v[86:87], 0, s[6:7]
	v_lshl_add_u64 v[20:21], v[74:75], 0, s[4:5]
	v_lshlrev_b64 v[20:21], 9, v[20:21]
	global_load_dwordx4 v[58:61], v[18:19], off nt
	global_load_dwordx4 v[50:53], v[18:19], off offset:1024 nt
	v_lshl_add_u64 v[18:19], v[84:85], 0, s[4:5]
	v_lshl_add_u64 v[20:21], v[80:81], 0, v[20:21]
	v_lshlrev_b64 v[18:19], 9, v[18:19]
	v_lshl_add_u64 v[18:19], v[80:81], 0, v[18:19]
	global_load_dwordx4 v[54:57], v[20:21], off nt
	global_load_dwordx4 v[46:49], v[18:19], off nt
	s_add_i32 s6, s12, s4
	s_cmp_lt_i32 s6, 0x8100
	v_mov_b32_e32 v91, 0
	s_cselect_b64 s[8:9], -1, 0
	s_cmp_gt_i32 s6, 0x80ff
	v_mov_b32_e32 v93, 0
	v_mov_b32_e32 v92, 0
	v_mov_b32_e32 v26, 0
	v_mov_b32_e32 v27, 0
	v_mov_b32_e32 v28, 0
	v_mov_b32_e32 v29, 0
	v_mov_b32_e32 v42, 0
	v_mov_b32_e32 v43, 0
	v_mov_b32_e32 v44, 0
	v_mov_b32_e32 v45, 0
	v_mov_b32_e32 v30, 0
	v_mov_b32_e32 v31, 0
	v_mov_b32_e32 v32, 0
	v_mov_b32_e32 v33, 0
	v_mov_b32_e32 v22, 0
	v_mov_b32_e32 v23, 0
	v_mov_b32_e32 v24, 0
	v_mov_b32_e32 v25, 0
	v_mov_b32_e32 v38, 0
	v_mov_b32_e32 v39, 0
	v_mov_b32_e32 v40, 0
	v_mov_b32_e32 v41, 0
	v_mov_b32_e32 v18, 0
	v_mov_b32_e32 v19, 0
	v_mov_b32_e32 v20, 0
	v_mov_b32_e32 v21, 0
	v_mov_b32_e32 v34, 0
	v_mov_b32_e32 v35, 0
	v_mov_b32_e32 v36, 0
	v_mov_b32_e32 v37, 0
	s_cbranch_scc1 .LBB0_1928
	s_ashr_i32 s7, s6, 31
	s_lshl_b64 s[14:15], s[6:7], 5
	v_lshl_add_u64 v[18:19], v[76:77], 0, s[14:15]
	s_add_u32 s14, s6, 0x8100
	s_addc_u32 s15, s7, 0
	s_lshl_b64 s[16:17], s[14:15], 5
	v_lshl_add_u64 v[20:21], v[76:77], 0, s[16:17]
	s_add_u32 s16, s6, 0x10200
	s_addc_u32 s17, s7, 0
	s_lshl_b64 s[18:19], s[16:17], 5
	v_lshl_add_u64 v[22:23], v[76:77], 0, s[18:19]
	s_lshl_b64 s[18:19], s[6:7], 10
	s_lshl_b64 s[14:15], s[14:15], 10
	v_lshl_add_u64 v[24:25], v[78:79], 0, s[18:19]
	global_load_dword v91, v[18:19], off
	global_load_dword v93, v[20:21], off
	global_load_dword v92, v[22:23], off
	global_load_dwordx4 v[26:29], v[24:25], off nt
	v_lshl_add_u64 v[18:19], v[78:79], 0, s[14:15]
	s_lshl_b64 s[14:15], s[16:17], 10
	v_lshl_add_u64 v[20:21], v[78:79], 0, s[14:15]
	s_lshl_b64 s[14:15], s[6:7], 11
	global_load_dwordx4 v[42:45], v[18:19], off nt
	global_load_dwordx4 v[30:33], v[20:21], off nt
	v_lshl_add_u64 v[18:19], v[86:87], 0, s[14:15]
	v_lshl_add_u64 v[20:21], v[74:75], 0, s[6:7]
	v_lshlrev_b64 v[20:21], 9, v[20:21]
	global_load_dwordx4 v[38:41], v[18:19], off nt
	global_load_dwordx4 v[22:25], v[18:19], off offset:1024 nt
	v_lshl_add_u64 v[18:19], v[84:85], 0, s[6:7]
	v_lshl_add_u64 v[98:99], v[80:81], 0, v[20:21]
	v_lshlrev_b64 v[18:19], 9, v[18:19]
	v_lshl_add_u64 v[100:101], v[80:81], 0, v[18:19]
	global_load_dwordx4 v[34:37], v[98:99], off nt
	global_load_dwordx4 v[18:21], v[100:101], off nt

; #define SUB(k, bit) (!(kargs()->li == 1 && (k) == lo) || ((kargs()->submask >> (bit)) & 1u))
; __global__ void __launch_bounds__(NWAVES * 64, 2) fwd(Args args_unused) {
;     ...
;             if (SUB(pb + 5, 1)) {
; #pragma unroll
;                 for (int q = 0; q < 2; ++q) { const f32x4 ga_ = *(const f32x4*)(A->in[I_GSSM] + l * DM + q * 512 + 8 * lane), gb_ = *(const f32x4*)(A->in[I_GSSM] + l * DM + q * 512 + 8 * lane + 4);
;                     gnv[q][0] = ga_.x; gnv[q][1] = ga_.y; gnv[q][2] = ga_.z; gnv[q][3] = ga_.w; gnv[q][4] = gb_.x; gnv[q][5] = gb_.y; gnv[q][6] = gb_.z; gnv[q][7] = gb_.w; } }
;             if (SUB(pb + 5, 1))
;             for (int row0 = gw; row0 < M; row0 += 2 * NGW) {
;                 const int hh = lane >> 3;
;                 float l0[2], l1[2], l2[2]; v4u r0[2], r1[2], r2[2], yr[2][2], zr[2][2];
; #pragma unroll
;                 for (int k = 0; k < 2; ++k) { const int row = row0 + k * NGW;
;                     l0[k] = 0.f; l1[k] = 0.f; l2[k] = 0.f; r0[k] = (v4u){0u, 0u, 0u, 0u}; r1[k] = (v4u){0u, 0u, 0u, 0u}; r2[k] = (v4u){0u, 0u, 0u, 0u};
.Lp8_post_3:
	s_cmp_eq_u32 s98, 1
	s_cbranch_scc1 .Lro_fin_3
	s_lshl_b32 s4, s33, 3
	s_add_i32 s4, s4, s62
	s_cmp_gt_i32 s4, 0x80ff
	s_cbranch_scc1 .LBB0_3954
	s_load_dwordx2 s[6:7], s[34:35], 0xc8
	v_lshlrev_b32_e32 v74, 5, v1
	v_mov_b32_e32 v75, 0
	s_mov_b64 s[8:9], 0x1000
	s_mov_b32 s5, 0x8100
	s_waitcnt lgkmcnt(0)
	v_lshl_add_u64 v[2:3], s[6:7], 0, v[74:75]
	v_lshl_add_u64 v[18:19], v[2:3], 0, s[8:9]
	v_add_co_u32_e32 v20, vcc, 0x1000, v2
	s_mov_b64 s[6:7], 0xb800000
	s_nop 0
	v_addc_co_u32_e32 v21, vcc, 0, v3, vcc
	global_load_dwordx4 v[2:5], v[18:19], off offset:16 nt
	global_load_dwordx4 v[6:9], v[18:19], off offset:2048 nt
	global_load_dwordx4 v[10:13], v[20:21], off nt
	global_load_dwordx4 v[14:17], v[18:19], off offset:2064 nt
	v_lshrrev_b32_e32 v18, 1, v1
	v_and_b32_e32 v74, 28, v18
	v_lshl_add_u64 v[18:19], s[30:31], 0, v[74:75]
	v_lshlrev_b32_e32 v74, 4, v1
	v_lshl_add_u64 v[76:77], v[18:19], 0, s[6:7]
	v_lshl_add_u64 v[18:19], s[30:31], 0, v[74:75]
	s_mov_b64 s[6:7], 0x67c00000
	v_lshl_add_u64 v[78:79], v[18:19], 0, s[6:7]
	s_mov_b64 s[6:7], 0x75e00000
	v_lshl_add_u64 v[82:83], v[18:19], 0, s[6:7]
	s_mov_b64 s[6:7], 0x6dd00000
	v_and_b32_e32 v74, 0x1f0, v74
	v_lshrrev_b32_e32 v1, 5, v1
	v_mov_b32_e32 v20, 0x91200
	v_lshl_add_u64 v[86:87], v[18:19], 0, s[6:7]
	s_mov_b64 s[6:7], 0x5fb00000
	v_lshl_add_u64 v[80:81], s[26:27], 0, v[74:75]
	v_mad_u32_u24 v74, v1, s5, v20
	v_mov_b32_e32 v20, 0xa1400
	v_lshl_add_u64 v[88:89], v[18:19], 0, s[6:7]
	v_mbcnt_lo_u32_b32 v18, -1, 0
	s_lshl_b32 s12, s3, 3
	v_mad_u32_u24 v84, v1, s5, v20
	v_mov_b32_e32 v85, v75
	s_lshl_b32 s3, s3, 4
	v_mov_b32_e32 v1, 0x358637bd
	v_mbcnt_hi_u32_b32 v90, -1, v18
	s_branch .LBB0_3950
